# baseline (speedup 1.0000x reference)
; #define LAS __attribute__((address_space(3)))
; #define SREP(bit) for (int rep_ = 0; rep_ < (((SUBDUP >> (bit)) & 1) ? 2 : 1); ++rep_)
; __device__ __forceinline__ void rw_scan4(const int tid, LAS float* lds, const float* RW, int task, int ntasks, int mode, const float* SIN, float* PQ, float* Y) {
;     const int slot = tid >> 7, sl = tid & 127, kp = sl & 7, rg = sl >> 3;
;     const bool active = task < ntasks;
;     int head = 0, c = 0, kind = 2;
;     if (active) { if (mode == 0) { kind = task & 1; head = (task >> 1) & 7; c = task >> 4; } else { head = task & 7; c = task >> 3; } }
;     const int t0 = c * CHL;
;     f32x2 s[4][4];
;     if (kind == 2 && active) {
;         const float* ip = SIN + (size_t)(head * NCH + c) * 4096 + (rg * 4) * 64 + kp * 8;
; #pragma unroll
;         for (int j = 0; j < 4; ++j) { const f32x4 i0 = *(const f32x4*)(ip + j * 64), i1 = *(const f32x4*)(ip + j * 64 + 4);
;             s[j][0] = (f32x2){i0.x, i0.y}; s[j][1] = (f32x2){i0.z, i0.w}; s[j][2] = (f32x2){i1.x, i1.y}; s[j][3] = (f32x2){i1.z, i1.w}; }
;     } else {
; #pragma unroll
;         for (int j = 0; j < 4; ++j)
; #pragma unroll
;             for (int i = 0; i < 4; ++i) { const int kk = kp * 8 + 2 * i, rr = rg * 4 + j; s[j][i] = (f32x2){(kind == 1 && kk == rr) ? 1.f : 0.f, (kind == 1 && kk + 1 == rr) ? 1.f : 0.f}; }
;     }
;     LAS float* sb = lds + slot * (2 * 6 * TB * 64);
;     const int srow = sl >> 4, sc4 = sl & 15;
;     const float* gsrc = RW + (size_t)(t0 + srow) * GW + head * 64 + sc4 * 4;
;     f32x4 st[6];
; __global__ void __launch_bounds__(NTHR, 2) hymba_fwd(Args args) {
;     ...
;             SREP(4) for (int tb = 0; tb < NCH * 8 * 2; tb += 4 * G) rw_scan4(tid, ldsf, WSP(float, WS_RW), tb + bid * 4 + (tid >> 7), NCH * 8 * 2, 0, nullptr, WSP(float, WS_PQ), nullptr);
.Lp6_entry:
	s_waitcnt vmcnt(5)
	v_and_b32_e32 v1, 7, v148
	s_waitcnt vmcnt(4)
	v_bfe_u32 v6, v148, 3, 4
	v_ashrrev_i32_e32 v0, 7, v148
	v_lshlrev_b32_e32 v2, 3, v1
	v_lshlrev_b32_e32 v3, 2, v6
	s_movk_i32 s4, 0x6000
	v_lshlrev_b32_e32 v130, 2, v148
	v_and_b32_e32 v131, 1, v0
	v_lshrrev_b32_e32 v132, 1, v0
	v_lshlrev_b32_e32 v131, 1, v131
	v_or_b32_e32 v131, v131, v132
	v_lshl_add_u32 v131, s44, 2, v131
	v_cmp_eq_u32_e64 s[38:39], v2, v3
	v_or_b32_e32 v2, 4, v2
	v_mul_lo_u32 v7, v0, s4
	v_bfe_u32 v133, v148, 4, 3
	v_and_b32_e32 v0, 60, v130
	v_readlane_b32 s0, v254, 32
	v_cmp_eq_u32_e64 s[40:41], v2, v3
	v_add_u32_e32 v3, 0, v7
	v_lshlrev_b32_e32 v4, 2, v0
	v_lshlrev_b32_e32 v2, 5, v1
	v_lshlrev_b32_e32 v1, 8, v133
	v_readlane_b32 s1, v254, 33
	v_add3_u32 v134, v3, v4, v1
	v_lshlrev_b32_e32 v4, 10, v6
	v_mov_b32_e32 v5, v144
	s_load_dwordx16 s[48:63], s[0:1], 0x38
	s_waitcnt lgkmcnt(0)
	v_lshl_add_u64 v[4:5], s[18:19], 0, v[4:5]
	v_mov_b32_e32 v3, v144
	v_lshl_add_u64 v[4:5], v[4:5], 0, v[2:3]
	s_mov_b64 s[4:5], 0x28300000
	s_add_u32 s0, s18, 0x16200000
	v_lshl_add_u64 v[92:93], v[4:5], 0, s[4:5]
	v_lshl_or_b32 v1, v6, 4, v7
	v_readlane_b32 s4, v254, 15
	s_addc_u32 s1, s19, 0
	s_lshl_b32 s14, s45, 2
	v_add_u32_e32 v135, s4, v1
	v_or_b32_e32 v1, v7, v2
	s_add_i32 s4, 0, 0x800
	v_cmp_eq_u32_e64 s[42:43], 1, v132
	v_add_u32_e32 v136, s4, v1
	s_mov_b32 s15, 0
	v_lshlrev_b32_e32 v94, 2, v0
	v_readlane_b32 s4, v255, 63
	s_cmp_lg_u32 s4, 0
	s_cbranch_scc1 .Lp6_go
	v_readlane_b32 s4, v254, 39
	s_bitcmp1_b32 s4, 3
	s_cbranch_scc1 .LBB0_251
.Lp6_go:
	s_branch .LBB0_214
.LBB0_213:
	s_or_b64 exec, exec, s[4:5]
	s_add_i32 s15, s15, s14
	s_cmpk_gt_i32 s15, 0x3ff
	s_cbranch_scc1 .LBB0_251

; #define SREP(bit) for (int rep_ = 0; rep_ < (((SUBDUP >> (bit)) & 1) ? 2 : 1); ++rep_)
; __global__ void __launch_bounds__(NTHR, 2) hymba_fwd(Args args) {
;     ...
;             __syncthreads();
;     ...
;             SREP(5) for (int u = bid; u < 32 * 16; u += G) s5_unit<true>(tid, ldsf, P, L, WSP(f32x2, WS_E), WSP(float, WS_VF), WSP(bf16, WS_VB), u);
.LBB0_251:
	v_readlane_b32 s0, v255, 63
	s_cmp_lg_u32 s0, 1
	s_cbranch_scc1 .Lp6_251_cont
	s_mov_b32 s0, 2
	s_nop 0
	v_writelane_b32 v255, s0, 63
	s_branch .LBB0_306

; __device__ __forceinline__ unsigned cvt_pk_bf16(float lo, float hi) { unsigned r; asm volatile("v_cvt_pk_bf16_f32 %0, %1, %2" : "=v"(r) : "v"(lo), "v"(hi)); return r; }
; __device__ __forceinline__ float geluf_(float y) { return y * sigmoidf_(1.5957691216057308f * (y + 0.044715f * y * y * y)); }
; #define SREP(bit) for (int rep_ = 0; rep_ < (((SUBDUP >> (bit)) & 1) ? 2 : 1); ++rep_)
; template <bool SECOND>
; __device__ __forceinline__ void s5_unit(const int tid, LAS float* ldsf, const float* P, const LayerP& L, f32x2* E, float* VF, bf16* VB, int unit) {
;     ...
;             for (int reg = 0; reg < 4; ++reg) {
;                 const int tk = tb * 16 + 4 * gq + reg;
;                 const float vv = geluf_(yacc[reg] + dch * uT[tk * 16 + r]);
;                 const size_t o = (size_t)(t0 + tk) * GW + g * 16 + r;
;                 VF[o] = vv;
;                 const float vn = __shfl_xor(vv, 1);
;                 if (!(r & 1)) *(unsigned*)(VB + o) = pg8::cvt_pk_bf16(vv, vn);
;             }
; __global__ void __launch_bounds__(NTHR, 2) hymba_fwd(Args args) {
;     ...
;             __syncthreads();
;             SREP(6) for (int sgi = bid; sgi < RGSEG; sgi += G) rg_scan_seg(tid, WSP(float, WS_RGA), WSP(float, WS_RGB), WSP(float, WS_RGC), WSP(float, WS_RGH), WSP(float, WS_SEG), sgi);
.LBB0_304:
	s_or_b64 exec, exec, s[0:1]
	ds_read_b32 v32, v100 offset:192
	s_waitcnt lgkmcnt(0)
	v_fmac_f32_e32 v35, v97, v32
	v_mul_f32_e32 v32, 0x3d372713, v35
	v_mul_f32_e32 v32, v35, v32
	v_fma_f32 v32, v35, v32, v35
	v_mul_f32_e32 v32, 0x3fcc422a, v32
	v_mul_f32_e32 v32, 0xbfb8aa3b, v32
	v_exp_f32_e32 v32, v32
	s_nop 0
	v_add_f32_e32 v32, 1.0, v32
	v_rcp_f32_e32 v32, v32
	s_nop 0
	v_mul_f32_e32 v34, v35, v32
	v_add_u32_e32 v32, 3, v92
	ds_bpermute_b32 v35, v99, v34
	v_ashrrev_i32_e32 v33, 31, v32
	v_lshlrev_b64 v[32:33], 9, v[32:33]
	v_lshl_add_u64 v[32:33], v[32:33], 0, v[90:91]
	v_lshl_add_u64 v[92:93], v[32:33], 2, s[20:21]
	global_store_dword v[92:93], v34, off
	s_and_saveexec_b64 s[0:1], s[46:47]
	s_cbranch_execz .LBB0_297
	v_lshl_add_u64 v[32:33], v[32:33], 1, s[22:23]
	s_waitcnt lgkmcnt(0)
	v_cvt_pk_bf16_f32 v34, v34, v35
	global_store_dword v[32:33], v34, off
	s_branch .LBB0_297
.LBB0_306:
	v_readlane_b32 s0, v255, 63
	s_cmp_lg_u32 s0, 0
	s_cbranch_scc1 .Lp6_306_cont
	v_readlane_b32 s0, v254, 39
	s_bitcmp1_b32 s0, 3
	s_cbranch_scc0 .Lp6_306_cont
	s_mov_b32 s0, 1
	s_nop 0
	v_writelane_b32 v255, s0, 63
	v_readlane_b32 s45, v254, 38
	v_readlane_b32 s44, v254, 39
	s_waitcnt vmcnt(0) lgkmcnt(0)
	s_barrier
	s_branch .Lp6_entry
.Lp6_306_cont:
	v_readlane_b32 s0, v254, 39
	s_cmpk_gt_i32 s0, 0x7f
	v_readlane_b32 s45, v254, 38
	s_waitcnt lgkmcnt(0)
	s_barrier
	s_cbranch_scc1 .LBB0_313
	v_readlane_b32 s44, v254, 39
	s_waitcnt vmcnt(0)
	v_cmp_gt_u32_e32 vcc, 0x80, v148
	s_and_saveexec_b64 s[4:5], vcc
	s_cbranch_execz .Lrgs_done
	v_lshlrev_b32_e32 v0, 4, v148
